# CONV loop: two trips per pass (both trips' 20 loads issued before a single vmcnt(0), second copy with renamed temporaries)
# baseline (speedup 1.0000x reference)
; __device__ __forceinline__ int tid_opaque() { int t = threadIdx.x; asm volatile("" : "+v"(t)); return t; }
; __device__ __forceinline__ void conv_phase(const Params& p) {
;     const bf16_t* TU = (const bf16_t*)(p.ws + WS_PROJ); bf16_t* Y = (bf16_t*)(p.ws + WS_H);
;     const int nth = gridDim.x * 512;
;     for (int idx = blockIdx.x * 512 + tid_opaque(); idx < MTOK * 128; idx += nth) {
;         const int row = idx >> 7, e = (idx & 127) * 8, s = row & (SEQ - 1);
;         const bf16_t* tp = TU + (size_t)row * 2048 + e;
;         const u32x4 t1 = *(const u32x4*)tp, uu = *(const u32x4*)(tp + 1024);
;         u32x4 t0 = (u32x4){0, 0, 0, 0}, t2 = (u32x4){0, 0, 0, 0};
;         if (s > 0) t0 = *(const u32x4*)(tp - 2048);
;         if (s < SEQ - 1) t2 = *(const u32x4*)(tp + 2048);
.LBB0_344:
	s_andn2_b64 vcc, exec, s[26:27]
	s_cbranch_vccnz .LBB0_353
	s_waitcnt lgkmcnt(0)
	v_mov_b32_e32 v2, v207
	v_readlane_b32 s2, v253, 12
	s_mov_b32 s4, 0x400000
	s_nop 0
	v_add_u32_e32 v1, s2, v2
	v_cmp_gt_i32_e32 vcc, s4, v1
	s_and_saveexec_b64 s[14:15], vcc
	s_cbranch_execz .LBB0_352
	v_readlane_b32 s2, v254, 50
	s_mov_b64 s[26:27], 0
	s_nop 0
	v_lshl_add_u32 v24, v2, 3, s2
	s_branch .LBB0_348
.LBB0_348:
	v_ashrrev_i32_e32 v18, 7, v1
	v_ashrrev_i32_e32 v19, 31, v18
	v_and_b32_e32 v25, 0x3f8, v24
	v_lshlrev_b64 v[2:3], 12, v[18:19]
	v_lshl_add_u64 v[2:3], s[84:85], 0, v[2:3]
	v_lshlrev_b32_e32 v20, 1, v25
	v_mov_b32_e32 v21, v0
	v_lshl_add_u64 v[22:23], v[2:3], 0, v[20:21]
	global_load_dwordx4 v[6:9], v[22:23], off
	global_load_dwordx4 v[10:13], v[22:23], off offset:2048
	v_and_b32_e32 v3, 0x1fff, v18
	v_mov_b32_e32 v2, 0
	v_cmp_ne_u32_e32 vcc, 0, v3
	v_mov_b32_e32 v14, 0
	v_mov_b32_e32 v15, 0
	v_mov_b32_e32 v16, 0
	v_mov_b32_e32 v17, 0
	s_and_saveexec_b64 s[40:41], vcc
	s_cbranch_execz .LBB0_350
	global_load_dwordx4 v[14:17], v[22:23], off offset:-4096

; __device__ __forceinline__ unsigned pk_bf16(float lo, float hi) { const f32x2 v = {lo, hi}; const bf16v2 b = __builtin_convertvector(v, bf16v2); return __builtin_bit_cast(unsigned, b); }
; __device__ __forceinline__ float bf_lo(unsigned u) { return __uint_as_float(u << 16); }
; __device__ __forceinline__ float bf_hi(unsigned u) { return __uint_as_float(u & 0xffff0000u); }
; __device__ __forceinline__ int tid_opaque() { int t = threadIdx.x; asm volatile("" : "+v"(t)); return t; }
; __device__ __forceinline__ void conv_phase(const Params& p) {
;     ...
;     for (int idx = blockIdx.x * 512 + tid_opaque(); idx < MTOK * 128; idx += nth) {
;         const int row = idx >> 7, e = (idx & 127) * 8, s = row & (SEQ - 1);
;         const bf16_t* tp = TU + (size_t)row * 2048 + e;
;         const u32x4 t1 = *(const u32x4*)tp, uu = *(const u32x4*)(tp + 1024);
;         u32x4 t0 = (u32x4){0, 0, 0, 0}, t2 = (u32x4){0, 0, 0, 0};
;         if (s > 0) t0 = *(const u32x4*)(tp - 2048);
;         if (s < SEQ - 1) t2 = *(const u32x4*)(tp + 2048);
;         const f32x4 k0a = *(const f32x4*)(p.conv_k + e), k0b = *(const f32x4*)(p.conv_k + e + 4), k1a = *(const f32x4*)(p.conv_k + 1024 + e), k1b = *(const f32x4*)(p.conv_k + 1024 + e + 4),
;                     k2a = *(const f32x4*)(p.conv_k + 2048 + e), k2b = *(const f32x4*)(p.conv_k + 2048 + e + 4);
;         u32x4 o;
; #pragma unroll
;         for (int j = 0; j < 4; ++j) {
;             const float ka0 = j < 2 ? k0a[2 * j] : k0b[2 * j - 4], kb0 = j < 2 ? k0a[2 * j + 1] : k0b[2 * j - 3];
;             const float ka1 = j < 2 ? k1a[2 * j] : k1b[2 * j - 4], kb1 = j < 2 ? k1a[2 * j + 1] : k1b[2 * j - 3];
;             const float ka2 = j < 2 ? k2a[2 * j] : k2b[2 * j - 4], kb2 = j < 2 ? k2a[2 * j + 1] : k2b[2 * j - 3];
;             const float lo = bf_lo(uu[j]) * (ka0 * bf_lo(t0[j]) + ka1 * bf_lo(t1[j]) + ka2 * bf_lo(t2[j]));
;             const float hi = bf_hi(uu[j]) * (kb0 * bf_hi(t0[j]) + kb1 * bf_hi(t1[j]) + kb2 * bf_hi(t2[j]));
;             o[j] = pk_bf16(lo, hi);
;         }
;         *(u32x4*)(Y + (size_t)row * DM + e) = o;
.Lcv_a2:
	s_or_b64 exec, exec, s[40:41]
	v_add_u32_e32 v1, s64, v1
	v_add_u32_e32 v24, s73, v24
	v_ashrrev_i32_e32 v78, 7, v1
	v_ashrrev_i32_e32 v79, 31, v78
	v_and_b32_e32 v85, 0x3f8, v24
	v_lshlrev_b64 v[62:63], 12, v[78:79]
	v_lshl_add_u64 v[62:63], s[84:85], 0, v[62:63]
	v_lshlrev_b32_e32 v80, 1, v85
	v_mov_b32_e32 v81, v0
	v_lshl_add_u64 v[82:83], v[62:63], 0, v[80:81]
	global_load_dwordx4 v[66:69], v[82:83], off
	global_load_dwordx4 v[70:73], v[82:83], off offset:2048
	v_and_b32_e32 v63, 0x1fff, v78
	v_mov_b32_e32 v62, 0
	v_cmp_ne_u32_e32 vcc, 0, v63
	v_mov_b32_e32 v74, 0
	v_mov_b32_e32 v75, 0
	v_mov_b32_e32 v76, 0
	v_mov_b32_e32 v77, 0
	s_and_saveexec_b64 s[40:41], vcc
	s_cbranch_execz .Lcv_b350
	global_load_dwordx4 v[74:77], v[82:83], off offset:-4096
.Lcv_b350:
	s_or_b64 exec, exec, s[40:41]
	v_cmp_ne_u32_e32 vcc, s72, v63
	v_mov_b32_e32 v63, 0
	v_mov_b32_e32 v64, 0
	v_mov_b32_e32 v65, 0
	s_and_saveexec_b64 s[40:41], vcc
	s_cbranch_execz .Lcv_b2
	v_add_co_u32_e32 v62, vcc, 0x1000, v82
	s_nop 1
	v_addc_co_u32_e32 v63, vcc, 0, v83, vcc
	global_load_dwordx4 v[62:65], v[62:63], off
	s_branch .Lcv_b2
.Lcv_b2:
	s_or_b64 exec, exec, s[40:41]
	v_add_u32_e32 v1, s64, v1
	v_add_u32_e32 v24, s73, v24
	v_readlane_b32 s4, v253, 27
	v_lshlrev_b32_e32 v21, 2, v25
	v_readlane_b32 s5, v253, 28
	s_nop 4
	global_load_dwordx4 v[26:29], v21, s[4:5] offset:16
	global_load_dwordx4 v[30:33], v21, s[4:5]
	v_readlane_b32 s4, v253, 25
	v_readlane_b32 s5, v253, 26
	s_nop 4
	global_load_dwordx4 v[34:37], v21, s[4:5] offset:16
	global_load_dwordx4 v[38:41], v21, s[4:5]
	v_readlane_b32 s4, v253, 29
	v_readlane_b32 s5, v253, 30
	s_nop 4
	global_load_dwordx4 v[42:45], v21, s[4:5] offset:16
	global_load_dwordx4 v[46:49], v21, s[4:5]
	v_readlane_b32 s4, v253, 27
	v_lshlrev_b32_e32 v81, 2, v85
	v_readlane_b32 s5, v253, 28
	s_nop 4
	global_load_dwordx4 v[86:89], v81, s[4:5] offset:16
	global_load_dwordx4 v[90:93], v81, s[4:5]
	v_readlane_b32 s4, v253, 25
	v_readlane_b32 s5, v253, 26
	s_nop 4
	global_load_dwordx4 v[94:97], v81, s[4:5] offset:16
	global_load_dwordx4 v[98:101], v81, s[4:5]
	v_readlane_b32 s4, v253, 29
	v_readlane_b32 s5, v253, 30
	s_nop 4
	global_load_dwordx4 v[102:105], v81, s[4:5] offset:16
	global_load_dwordx4 v[106:109], v81, s[4:5]
	s_waitcnt vmcnt(0)
	v_lshlrev_b32_e32 v52, 16, v6
	v_and_b32_e32 v53, 0xffff0000, v6
	v_lshlrev_b32_e32 v6, 16, v7
	v_and_b32_e32 v7, 0xffff0000, v7
	v_lshlrev_b32_e32 v50, 16, v14
	v_and_b32_e32 v51, 0xffff0000, v14
	v_lshlrev_b32_e32 v14, 16, v15
	v_and_b32_e32 v15, 0xffff0000, v15
	v_lshlrev_b32_e32 v22, 16, v10
	v_and_b32_e32 v23, 0xffff0000, v10
	v_lshlrev_b32_e32 v10, 16, v11
	v_and_b32_e32 v11, 0xffff0000, v11
	v_mov_b32_e32 v21, v0
	v_pk_mul_f32 v[6:7], v[40:41], v[6:7]
	s_nop 0
	v_pk_fma_f32 v[6:7], v[32:33], v[14:15], v[6:7]
	v_lshlrev_b32_e32 v14, 16, v3
	v_and_b32_e32 v15, 0xffff0000, v3
	v_pk_fma_f32 v[6:7], v[48:49], v[14:15], v[6:7]
	v_lshlrev_b32_e32 v14, 16, v8
	v_and_b32_e32 v15, 0xffff0000, v8
	v_pk_mul_f32 v[6:7], v[6:7], v[10:11]
	v_lshlrev_b32_e32 v10, 16, v16
	v_and_b32_e32 v11, 0xffff0000, v16
	v_pk_mul_f32 v[14:15], v[34:35], v[14:15]
	v_cvt_pk_bf16_f32 v3, v6, v7
	v_pk_fma_f32 v[10:11], v[26:27], v[10:11], v[14:15]
	v_lshlrev_b32_e32 v14, 16, v4
	v_and_b32_e32 v15, 0xffff0000, v4
	v_lshlrev_b32_e32 v6, 16, v12
	v_and_b32_e32 v7, 0xffff0000, v12
	v_pk_fma_f32 v[10:11], v[42:43], v[14:15], v[10:11]
	v_lshlrev_b32_e32 v8, 16, v9
	v_and_b32_e32 v9, 0xffff0000, v9
	v_pk_mul_f32 v[6:7], v[10:11], v[6:7]
	v_lshlrev_b32_e32 v10, 16, v17
	v_and_b32_e32 v11, 0xffff0000, v17
	v_pk_mul_f32 v[8:9], v[36:37], v[8:9]
	v_pk_mul_f32 v[38:39], v[38:39], v[52:53]
	v_pk_fma_f32 v[8:9], v[28:29], v[10:11], v[8:9]
	v_lshlrev_b32_e32 v10, 16, v5
	v_and_b32_e32 v11, 0xffff0000, v5
	v_cvt_pk_bf16_f32 v4, v6, v7
	v_lshlrev_b32_e32 v6, 16, v13
	v_and_b32_e32 v7, 0xffff0000, v13
	v_pk_fma_f32 v[8:9], v[44:45], v[10:11], v[8:9]
	v_pk_fma_f32 v[30:31], v[30:31], v[50:51], v[38:39]
	v_lshlrev_b32_e32 v38, 16, v2
	v_and_b32_e32 v39, 0xffff0000, v2
	v_pk_mul_f32 v[6:7], v[8:9], v[6:7]
	v_pk_fma_f32 v[30:31], v[46:47], v[38:39], v[30:31]
	v_cvt_pk_bf16_f32 v5, v6, v7
	v_lshlrev_b64 v[6:7], 11, v[18:19]
	v_pk_mul_f32 v[22:23], v[30:31], v[22:23]
	v_lshl_add_u64 v[6:7], s[80:81], 0, v[6:7]
	v_cvt_pk_bf16_f32 v2, v22, v23
	v_lshl_add_u64 v[6:7], v[6:7], 0, v[20:21]
	global_store_dwordx4 v[6:7], v[2:5], off
	v_lshlrev_b32_e32 v112, 16, v66
	v_and_b32_e32 v113, 0xffff0000, v66
	v_lshlrev_b32_e32 v66, 16, v67
	v_and_b32_e32 v67, 0xffff0000, v67
	v_lshlrev_b32_e32 v110, 16, v74
	v_and_b32_e32 v111, 0xffff0000, v74
	v_lshlrev_b32_e32 v74, 16, v75
	v_and_b32_e32 v75, 0xffff0000, v75
	v_lshlrev_b32_e32 v82, 16, v70
	v_and_b32_e32 v83, 0xffff0000, v70
	v_lshlrev_b32_e32 v70, 16, v71
	v_and_b32_e32 v71, 0xffff0000, v71
	v_mov_b32_e32 v81, v0
	v_pk_mul_f32 v[66:67], v[100:101], v[66:67]
	s_nop 0
	v_pk_fma_f32 v[66:67], v[92:93], v[74:75], v[66:67]
	v_lshlrev_b32_e32 v74, 16, v63
	v_and_b32_e32 v75, 0xffff0000, v63
	v_pk_fma_f32 v[66:67], v[108:109], v[74:75], v[66:67]
	v_lshlrev_b32_e32 v74, 16, v68
	v_and_b32_e32 v75, 0xffff0000, v68
	v_pk_mul_f32 v[66:67], v[66:67], v[70:71]
	v_lshlrev_b32_e32 v70, 16, v76
	v_and_b32_e32 v71, 0xffff0000, v76
	v_pk_mul_f32 v[74:75], v[94:95], v[74:75]
	v_cvt_pk_bf16_f32 v63, v66, v67
	v_pk_fma_f32 v[70:71], v[86:87], v[70:71], v[74:75]
	v_lshlrev_b32_e32 v74, 16, v64
	v_and_b32_e32 v75, 0xffff0000, v64
	v_lshlrev_b32_e32 v66, 16, v72
	v_and_b32_e32 v67, 0xffff0000, v72
	v_pk_fma_f32 v[70:71], v[102:103], v[74:75], v[70:71]
	v_lshlrev_b32_e32 v68, 16, v69
	v_and_b32_e32 v69, 0xffff0000, v69
	v_pk_mul_f32 v[66:67], v[70:71], v[66:67]
	v_lshlrev_b32_e32 v70, 16, v77
	v_and_b32_e32 v71, 0xffff0000, v77
	v_pk_mul_f32 v[68:69], v[96:97], v[68:69]
	v_pk_mul_f32 v[98:99], v[98:99], v[112:113]
	v_pk_fma_f32 v[68:69], v[88:89], v[70:71], v[68:69]
	v_lshlrev_b32_e32 v70, 16, v65
	v_and_b32_e32 v71, 0xffff0000, v65
	v_cvt_pk_bf16_f32 v64, v66, v67
	v_lshlrev_b32_e32 v66, 16, v73
	v_and_b32_e32 v67, 0xffff0000, v73
	v_pk_fma_f32 v[68:69], v[104:105], v[70:71], v[68:69]
	v_pk_fma_f32 v[90:91], v[90:91], v[110:111], v[98:99]
	v_lshlrev_b32_e32 v98, 16, v62
	v_and_b32_e32 v99, 0xffff0000, v62
	v_pk_mul_f32 v[66:67], v[68:69], v[66:67]
	v_pk_fma_f32 v[90:91], v[106:107], v[98:99], v[90:91]
	v_cvt_pk_bf16_f32 v65, v66, v67
	v_lshlrev_b64 v[66:67], 11, v[78:79]
	v_pk_mul_f32 v[82:83], v[90:91], v[82:83]
	v_lshl_add_u64 v[66:67], s[80:81], 0, v[66:67]
	v_cvt_pk_bf16_f32 v62, v82, v83
	v_lshl_add_u64 v[66:67], v[66:67], 0, v[80:81]
	global_store_dwordx4 v[66:67], v[62:65], off
	s_mov_b32 s4, 0x3fffff
	v_cmp_lt_i32_e32 vcc, s4, v1
	s_or_b64 s[26:27], vcc, s[26:27]
	s_andn2_b64 exec, exec, s[26:27]
	s_cbranch_execz .LBB0_352
	s_branch .LBB0_348
